# 64-byte alignment (nop fill) of the merge and out-proj K-loop headers (on top of v54)
# baseline (speedup 1.0000x reference)
; template <class Epi, class Sched>
; __device__ __forceinline__ void gemm_phase(LAS unsigned char* lds, const int lda, const int ldb, const Sched& S, const Epi& E) {
;     ...
;         const int nt = cur.nt;
;         for (int t = 0; t < nt; t += 2) {
;             const bool last = (t == nt - 2);
;             const char* a1 = cA + (size_t)(t + 1) * kstep;
;             const char* a2 = last ? nA : cA + (size_t)(t + 2) * kstep; const char* b2 = last ? nB : cB + (size_t)(t + 2) * kstep;
;     ...
;         for (int a = 0; a < 2; ++a)
; #pragma unroll
;             for (int b = 0; b < 2; ++b)
; #pragma unroll
;                 for (int m = 0; m < 4; ++m)
; #pragma unroll
;                     for (int n = 0; n < 2; ++n) acc[a][b][m][n] = (f32x4){0.f, 0.f, 0.f, 0.f};
;         cur = nxt; cA = nA; cB = nB; ++ui;
.LBB0_661:
	s_add_i32 s24, s59, -2
	s_add_u32 s25, s36, 0x100
	v_mov_b32_e32 v2, 0
	s_addc_u32 s60, s37, 0
	s_mov_b32 s44, 0
	v_mov_b32_e32 v3, v2
	v_mov_b32_e32 v4, v2
	v_mov_b32_e32 v5, v2
	v_mov_b32_e32 v6, v2
	v_mov_b32_e32 v7, v2
	v_mov_b32_e32 v8, v2
	v_mov_b32_e32 v9, v2
	v_mov_b32_e32 v18, v2
	v_mov_b32_e32 v19, v2
	v_mov_b32_e32 v20, v2
	v_mov_b32_e32 v21, v2
	v_mov_b32_e32 v22, v2
	v_mov_b32_e32 v23, v2
	v_mov_b32_e32 v24, v2
	v_mov_b32_e32 v25, v2
	v_mov_b32_e32 v34, v2
	v_mov_b32_e32 v35, v2
	v_mov_b32_e32 v36, v2
	v_mov_b32_e32 v37, v2
	v_mov_b32_e32 v38, v2
	v_mov_b32_e32 v39, v2
	v_mov_b32_e32 v40, v2
	v_mov_b32_e32 v41, v2
	v_mov_b32_e32 v50, v2
	v_mov_b32_e32 v51, v2
	v_mov_b32_e32 v52, v2
	v_mov_b32_e32 v53, v2
	v_mov_b32_e32 v54, v2
	v_mov_b32_e32 v55, v2
	v_mov_b32_e32 v56, v2
	v_mov_b32_e32 v57, v2
	v_mov_b32_e32 v10, v2
	v_mov_b32_e32 v11, v2
	v_mov_b32_e32 v12, v2
	v_mov_b32_e32 v13, v2
	v_mov_b32_e32 v14, v2
	v_mov_b32_e32 v15, v2
	v_mov_b32_e32 v16, v2
	v_mov_b32_e32 v17, v2
	v_mov_b32_e32 v26, v2
	v_mov_b32_e32 v27, v2
	v_mov_b32_e32 v28, v2
	v_mov_b32_e32 v29, v2
	v_mov_b32_e32 v30, v2
	v_mov_b32_e32 v31, v2
	v_mov_b32_e32 v32, v2
	v_mov_b32_e32 v33, v2
	v_mov_b32_e32 v42, v2
	v_mov_b32_e32 v43, v2
	v_mov_b32_e32 v44, v2
	v_mov_b32_e32 v45, v2
	v_mov_b32_e32 v46, v2
	v_mov_b32_e32 v47, v2
	v_mov_b32_e32 v48, v2
	v_mov_b32_e32 v49, v2
	v_mov_b32_e32 v58, v2
	v_mov_b32_e32 v59, v2
	v_mov_b32_e32 v60, v2
	v_mov_b32_e32 v61, v2
	v_mov_b32_e32 v62, v2
	v_mov_b32_e32 v63, v2
	v_mov_b32_e32 v64, v2
	v_mov_b32_e32 v65, v2
	v_mov_b32_e32 v66, v2
	v_mov_b32_e32 v67, v2
	v_mov_b32_e32 v68, v2
	v_mov_b32_e32 v69, v2
	v_mov_b32_e32 v70, v2
	v_mov_b32_e32 v71, v2
	v_mov_b32_e32 v72, v2
	v_mov_b32_e32 v73, v2
	v_mov_b32_e32 v82, v2
	v_mov_b32_e32 v83, v2
	v_mov_b32_e32 v84, v2
	v_mov_b32_e32 v85, v2
	v_mov_b32_e32 v86, v2
	v_mov_b32_e32 v87, v2
	v_mov_b32_e32 v88, v2
	v_mov_b32_e32 v89, v2
	v_mov_b32_e32 v98, v2
	v_mov_b32_e32 v99, v2
	v_mov_b32_e32 v100, v2
	v_mov_b32_e32 v101, v2
	v_mov_b32_e32 v102, v2
	v_mov_b32_e32 v103, v2
	v_mov_b32_e32 v104, v2
	v_mov_b32_e32 v105, v2
	v_mov_b32_e32 v114, v2
	v_mov_b32_e32 v115, v2
	v_mov_b32_e32 v116, v2
	v_mov_b32_e32 v117, v2
	s_waitcnt vmcnt(0)
	v_mov_b32_e32 v118, v2
	v_mov_b32_e32 v119, v2
	v_mov_b32_e32 v120, v2
	v_mov_b32_e32 v121, v2
	v_mov_b32_e32 v74, v2
	v_mov_b32_e32 v75, v2
	v_mov_b32_e32 v76, v2
	v_mov_b32_e32 v77, v2
	v_mov_b32_e32 v78, v2
	v_mov_b32_e32 v79, v2
	v_mov_b32_e32 v80, v2
	v_mov_b32_e32 v81, v2
	v_mov_b32_e32 v90, v2
	v_mov_b32_e32 v91, v2
	v_mov_b32_e32 v92, v2
	v_mov_b32_e32 v93, v2
	v_mov_b32_e32 v94, v2
	v_mov_b32_e32 v95, v2
	v_mov_b32_e32 v96, v2
	v_mov_b32_e32 v97, v2
	v_mov_b32_e32 v106, v2
	v_mov_b32_e32 v107, v2
	v_mov_b32_e32 v108, v2
	v_mov_b32_e32 v109, v2
	v_mov_b32_e32 v110, v2
	v_mov_b32_e32 v111, v2
	v_mov_b32_e32 v112, v2
	v_mov_b32_e32 v113, v2
	v_mov_b32_e32 v122, v2
	v_mov_b32_e32 v123, v2
	v_mov_b32_e32 v124, v2
	v_mov_b32_e32 v125, v2
	v_mov_b32_e32 v126, v2
	v_mov_b32_e32 v127, v2
	v_mov_b32_e32 v128, v2
	v_mov_b32_e32 v129, v2
	.p2align 6

; template <class Epi, class Sched>
; __device__ __forceinline__ void gemm_phase(LAS unsigned char* lds, const int lda, const int ldb, const Sched& S, const Epi& E) {
;     ...
;         const int nt = cur.nt;
;         for (int t = 0; t < nt; t += 2) {
;             const bool last = (t == nt - 2);
;             const char* a1 = cA + (size_t)(t + 1) * kstep;
;             const char* a2 = last ? nA : cA + (size_t)(t + 2) * kstep; const char* b2 = last ? nB : cB + (size_t)(t + 2) * kstep;
;     ...
;         for (int a = 0; a < 2; ++a)
; #pragma unroll
;             for (int b = 0; b < 2; ++b)
; #pragma unroll
;                 for (int m = 0; m < 4; ++m)
; #pragma unroll
;                     for (int n = 0; n < 2; ++n) acc[a][b][m][n] = (f32x4){0.f, 0.f, 0.f, 0.f};
;         cur = nxt; cA = nA; cB = nB; ++ui;
.LBB0_801:
	s_add_u32 s17, s36, 0x100
	v_mov_b32_e32 v2, 0
	s_addc_u32 s24, s37, 0
	s_mov_b32 s25, -2
	s_waitcnt lgkmcnt(0)
	v_mov_b32_e32 v3, v2
	v_mov_b32_e32 v4, v2
	v_mov_b32_e32 v5, v2
	v_mov_b32_e32 v6, v2
	v_mov_b32_e32 v7, v2
	v_mov_b32_e32 v8, v2
	v_mov_b32_e32 v9, v2
	v_mov_b32_e32 v18, v2
	v_mov_b32_e32 v19, v2
	v_mov_b32_e32 v20, v2
	v_mov_b32_e32 v21, v2
	v_mov_b32_e32 v22, v2
	v_mov_b32_e32 v23, v2
	v_mov_b32_e32 v24, v2
	v_mov_b32_e32 v25, v2
	v_mov_b32_e32 v34, v2
	v_mov_b32_e32 v35, v2
	v_mov_b32_e32 v36, v2
	v_mov_b32_e32 v37, v2
	v_mov_b32_e32 v38, v2
	v_mov_b32_e32 v39, v2
	v_mov_b32_e32 v40, v2
	v_mov_b32_e32 v41, v2
	v_mov_b32_e32 v50, v2
	v_mov_b32_e32 v51, v2
	v_mov_b32_e32 v52, v2
	v_mov_b32_e32 v53, v2
	v_mov_b32_e32 v54, v2
	v_mov_b32_e32 v55, v2
	v_mov_b32_e32 v56, v2
	v_mov_b32_e32 v57, v2
	v_mov_b32_e32 v10, v2
	v_mov_b32_e32 v11, v2
	v_mov_b32_e32 v12, v2
	v_mov_b32_e32 v13, v2
	v_mov_b32_e32 v14, v2
	v_mov_b32_e32 v15, v2
	v_mov_b32_e32 v16, v2
	v_mov_b32_e32 v17, v2
	v_mov_b32_e32 v26, v2
	v_mov_b32_e32 v27, v2
	v_mov_b32_e32 v28, v2
	v_mov_b32_e32 v29, v2
	v_mov_b32_e32 v30, v2
	v_mov_b32_e32 v31, v2
	v_mov_b32_e32 v32, v2
	v_mov_b32_e32 v33, v2
	v_mov_b32_e32 v42, v2
	v_mov_b32_e32 v43, v2
	v_mov_b32_e32 v44, v2
	v_mov_b32_e32 v45, v2
	v_mov_b32_e32 v46, v2
	v_mov_b32_e32 v47, v2
	v_mov_b32_e32 v48, v2
	v_mov_b32_e32 v49, v2
	v_mov_b32_e32 v58, v2
	v_mov_b32_e32 v59, v2
	v_mov_b32_e32 v60, v2
	v_mov_b32_e32 v61, v2
	v_mov_b32_e32 v62, v2
	v_mov_b32_e32 v63, v2
	v_mov_b32_e32 v64, v2
	v_mov_b32_e32 v65, v2
	v_mov_b32_e32 v66, v2
	v_mov_b32_e32 v67, v2
	v_mov_b32_e32 v68, v2
	v_mov_b32_e32 v69, v2
	v_mov_b32_e32 v70, v2
	v_mov_b32_e32 v71, v2
	v_mov_b32_e32 v72, v2
	v_mov_b32_e32 v73, v2
	v_mov_b32_e32 v82, v2
	v_mov_b32_e32 v83, v2
	v_mov_b32_e32 v84, v2
	v_mov_b32_e32 v85, v2
	v_mov_b32_e32 v86, v2
	v_mov_b32_e32 v87, v2
	v_mov_b32_e32 v88, v2
	v_mov_b32_e32 v89, v2
	v_mov_b32_e32 v98, v2
	v_mov_b32_e32 v99, v2
	v_mov_b32_e32 v100, v2
	v_mov_b32_e32 v101, v2
	v_mov_b32_e32 v102, v2
	v_mov_b32_e32 v103, v2
	v_mov_b32_e32 v104, v2
	v_mov_b32_e32 v105, v2
	v_mov_b32_e32 v114, v2
	v_mov_b32_e32 v115, v2
	v_mov_b32_e32 v116, v2
	v_mov_b32_e32 v117, v2
	v_mov_b32_e32 v118, v2
	v_mov_b32_e32 v119, v2
	v_mov_b32_e32 v120, v2
	v_mov_b32_e32 v121, v2
	v_mov_b32_e32 v74, v2
	v_mov_b32_e32 v75, v2
	v_mov_b32_e32 v76, v2
	v_mov_b32_e32 v77, v2
	v_mov_b32_e32 v78, v2
	v_mov_b32_e32 v79, v2
	v_mov_b32_e32 v80, v2
	v_mov_b32_e32 v81, v2
	v_mov_b32_e32 v90, v2
	v_mov_b32_e32 v91, v2
	v_mov_b32_e32 v92, v2
	v_mov_b32_e32 v93, v2
	v_mov_b32_e32 v94, v2
	v_mov_b32_e32 v95, v2
	v_mov_b32_e32 v96, v2
	v_mov_b32_e32 v97, v2
	v_mov_b32_e32 v106, v2
	v_mov_b32_e32 v107, v2
	v_mov_b32_e32 v108, v2
	v_mov_b32_e32 v109, v2
	v_mov_b32_e32 v110, v2
	v_mov_b32_e32 v111, v2
	v_mov_b32_e32 v112, v2
	v_mov_b32_e32 v113, v2
	v_mov_b32_e32 v122, v2
	v_mov_b32_e32 v123, v2
	v_mov_b32_e32 v124, v2
	v_mov_b32_e32 v125, v2
	v_mov_b32_e32 v126, v2
	v_mov_b32_e32 v127, v2
	v_mov_b32_e32 v128, v2
	v_mov_b32_e32 v129, v2
	.p2align 6
